# best + prologue K-tile-1 DMAs issued before the first wait + unit-head spurious vmcnt(0) removed, K-loop heads re-padded to the same placement
# baseline (speedup 1.0000x reference)
.LBB0_149:
	s_ashr_i32 s79, s78, 31
	s_lshl_b64 s[6:7], s[78:79], 11
	s_add_u32 s82, s34, s6
	s_addc_u32 s83, s35, s7
	s_and_b64 s[6:7], s[0:1], exec
	s_cselect_b32 s8, s83, s3
	s_cselect_b32 s9, s82, s2
	s_ashr_i32 s81, s80, 31
	s_lshl_b64 s[6:7], s[80:81], 11
	s_add_u32 s84, s40, s6
	s_addc_u32 s85, s41, s7
	s_and_b64 s[6:7], s[0:1], exec
	s_cselect_b32 s79, s85, s5
	s_cselect_b32 s81, s84, s4
	s_add_u32 s2, s2, 0x40080
	s_addc_u32 s3, s3, 0
	s_add_u32 s87, s4, 0x100
	v_mov_b32_e32 v0, 0
	s_addc_u32 s88, s5, 0
	s_mov_b32 s89, -2
	v_mov_b32_e32 v1, v0
	v_mov_b32_e32 v2, v0
	v_mov_b32_e32 v3, v0
	v_mov_b32_e32 v4, v0
	v_mov_b32_e32 v5, v0
	v_mov_b32_e32 v6, v0
	v_mov_b32_e32 v7, v0
	v_mov_b32_e32 v16, v0
	v_mov_b32_e32 v17, v0
	v_mov_b32_e32 v18, v0
	v_mov_b32_e32 v19, v0
	v_mov_b32_e32 v20, v0
	v_mov_b32_e32 v21, v0
	v_mov_b32_e32 v22, v0
	v_mov_b32_e32 v23, v0
	v_mov_b32_e32 v32, v0
	v_mov_b32_e32 v33, v0
	v_mov_b32_e32 v34, v0
	v_mov_b32_e32 v35, v0

	v_mov_b64_e32 v[8:9], 0
	v_mov_b64_e32 v[10:11], 0
	v_mov_b64_e32 v[12:13], 0
	v_mov_b64_e32 v[14:15], 0
	v_mov_b64_e32 v[24:25], 0
	v_mov_b64_e32 v[26:27], 0
	v_mov_b64_e32 v[28:29], 0
	v_mov_b64_e32 v[30:31], 0
	v_mov_b64_e32 v[36:37], 0
	v_mov_b64_e32 v[38:39], 0
	v_mov_b64_e32 v[40:41], 0
	v_mov_b64_e32 v[42:43], 0
	v_mov_b64_e32 v[44:45], 0
	v_mov_b64_e32 v[46:47], 0
	v_mov_b64_e32 v[64:65], 0
	v_mov_b64_e32 v[66:67], 0
	v_mov_b64_e32 v[68:69], 0
	v_mov_b64_e32 v[70:71], 0
	v_mov_b64_e32 v[72:73], 0
	v_mov_b64_e32 v[74:75], 0
	v_mov_b64_e32 v[76:77], 0
	v_mov_b64_e32 v[78:79], 0
	v_mov_b64_e32 v[80:81], 0
	v_mov_b64_e32 v[82:83], 0
	v_mov_b64_e32 v[84:85], 0
	v_mov_b64_e32 v[86:87], 0
	v_mov_b64_e32 v[88:89], 0
	v_mov_b64_e32 v[90:91], 0
	v_mov_b64_e32 v[92:93], 0
	v_mov_b64_e32 v[94:95], 0
	v_mov_b64_e32 v[96:97], 0
	v_mov_b64_e32 v[98:99], 0
	v_mov_b64_e32 v[100:101], 0
	v_mov_b64_e32 v[102:103], 0
	v_mov_b64_e32 v[104:105], 0
	v_mov_b64_e32 v[106:107], 0
	v_mov_b64_e32 v[108:109], 0
	v_mov_b64_e32 v[110:111], 0
	v_mov_b64_e32 v[112:113], 0
	v_mov_b64_e32 v[114:115], 0
	v_mov_b64_e32 v[116:117], 0
	v_mov_b64_e32 v[118:119], 0
	v_mov_b64_e32 v[120:121], 0
	v_mov_b64_e32 v[122:123], 0
	v_mov_b64_e32 v[124:125], 0
	v_mov_b64_e32 v[126:127], 0
	v_mov_b64_e32 v[128:129], 0
	v_mov_b64_e32 v[130:131], 0
	v_mov_b64_e32 v[132:133], 0
	v_mov_b64_e32 v[134:135], 0
	v_mov_b64_e32 v[136:137], 0
	v_mov_b64_e32 v[138:139], 0
	v_mov_b64_e32 v[140:141], 0
	v_mov_b64_e32 v[142:143], 0
	s_nop 0
	s_nop 0
	s_nop 0
	s_nop 0
	s_nop 0
	s_nop 0
	s_nop 0
	s_nop 0
	s_nop 0
	s_nop 0
	s_nop 0
	s_nop 0
	s_nop 0

.LBB0_740:
	s_ashr_i32 s11, s10, 31
	v_cmp_lt_i64_e32 vcc, s[14:15], v[164:165]
	s_lshl_b64 s[14:15], s[10:11], 11
	s_add_u32 s14, s41, s14
	s_addc_u32 s15, s54, s15
	s_and_b64 s[18:19], vcc, exec
	s_cselect_b32 s6, s15, s53
	s_cselect_b32 s11, s14, s52
	s_ashr_i32 s13, s12, 31
	s_lshl_b64 s[18:19], s[12:13], 11
	s_add_u32 s18, s55, s18
	s_addc_u32 s19, s56, s19
	s_and_b64 s[60:61], vcc, exec
	s_cselect_b32 s13, s19, s59
	s_cselect_b32 s80, s18, s58
	s_add_u32 s52, s52, 0x40080
	s_addc_u32 s53, s53, 0
	s_add_u32 s81, s58, 0x100
	v_mov_b32_e32 v0, 0
	s_addc_u32 s82, s59, 0
	s_mov_b32 s83, -2
	s_waitcnt lgkmcnt(0)
	v_mov_b32_e32 v1, v0
	v_mov_b32_e32 v2, v0
	v_mov_b32_e32 v3, v0
	v_mov_b32_e32 v4, v0
	v_mov_b32_e32 v5, v0
	v_mov_b32_e32 v6, v0
	v_mov_b32_e32 v7, v0
	v_mov_b32_e32 v16, v0
	v_mov_b32_e32 v17, v0
	v_mov_b32_e32 v18, v0
	v_mov_b32_e32 v19, v0
	v_mov_b32_e32 v20, v0
	v_mov_b32_e32 v21, v0
	v_mov_b32_e32 v22, v0
	v_mov_b32_e32 v23, v0
	v_mov_b32_e32 v32, v0
	v_mov_b32_e32 v33, v0
	v_mov_b32_e32 v34, v0
	v_mov_b32_e32 v35, v0

	v_mov_b64_e32 v[8:9], 0
	v_mov_b64_e32 v[10:11], 0
	v_mov_b64_e32 v[12:13], 0
	v_mov_b64_e32 v[14:15], 0
	v_mov_b64_e32 v[24:25], 0
	v_mov_b64_e32 v[26:27], 0
	v_mov_b64_e32 v[28:29], 0
	v_mov_b64_e32 v[30:31], 0
	v_mov_b64_e32 v[36:37], 0
	v_mov_b64_e32 v[38:39], 0
	v_mov_b64_e32 v[40:41], 0
	v_mov_b64_e32 v[42:43], 0
	v_mov_b64_e32 v[44:45], 0
	v_mov_b64_e32 v[46:47], 0
	v_mov_b64_e32 v[48:49], 0
	v_mov_b64_e32 v[50:51], 0
	v_mov_b64_e32 v[52:53], 0
	v_mov_b64_e32 v[54:55], 0
	v_mov_b64_e32 v[56:57], 0
	v_mov_b64_e32 v[58:59], 0
	v_mov_b64_e32 v[60:61], 0
	v_mov_b64_e32 v[62:63], 0
	v_mov_b64_e32 v[64:65], 0
	v_mov_b64_e32 v[66:67], 0
	v_mov_b64_e32 v[68:69], 0
	v_mov_b64_e32 v[70:71], 0
	v_mov_b64_e32 v[72:73], 0
	v_mov_b64_e32 v[74:75], 0
	v_mov_b64_e32 v[76:77], 0
	v_mov_b64_e32 v[78:79], 0
	v_mov_b64_e32 v[80:81], 0
	v_mov_b64_e32 v[82:83], 0
	v_mov_b64_e32 v[84:85], 0
	v_mov_b64_e32 v[86:87], 0
	v_mov_b64_e32 v[88:89], 0
	v_mov_b64_e32 v[90:91], 0
	v_mov_b64_e32 v[92:93], 0
	v_mov_b64_e32 v[94:95], 0
	v_mov_b64_e32 v[96:97], 0
	v_mov_b64_e32 v[98:99], 0
	v_mov_b64_e32 v[100:101], 0
	v_mov_b64_e32 v[102:103], 0
	v_mov_b64_e32 v[104:105], 0
	v_mov_b64_e32 v[106:107], 0
	v_mov_b64_e32 v[108:109], 0
	v_mov_b64_e32 v[110:111], 0
	v_mov_b64_e32 v[112:113], 0
	v_mov_b64_e32 v[114:115], 0
	v_mov_b64_e32 v[116:117], 0
	v_mov_b64_e32 v[118:119], 0
	v_mov_b64_e32 v[120:121], 0
	v_mov_b64_e32 v[122:123], 0
	v_mov_b64_e32 v[124:125], 0
	v_mov_b64_e32 v[126:127], 0
	s_nop 0
	s_nop 0
	s_nop 0
	s_nop 0
	s_nop 0
	s_nop 0
	s_nop 0
	s_nop 0
	s_nop 0
	s_nop 0
	s_nop 0
	s_nop 0
	s_nop 0

.LBB0_874:
	s_ashr_i32 s61, s60, 31
	s_lshl_b64 s[66:67], s[60:61], 11
	s_add_u32 s66, s34, s66
	s_addc_u32 s67, s35, s67
	s_and_b64 s[68:69], s[62:63], exec
	s_cselect_b32 s3, s67, s85
	s_cselect_b32 s61, s66, s84
	s_ashr_i32 s65, s64, 31
	s_lshl_b64 s[68:69], s[64:65], 11
	s_add_u32 s78, s19, s68
	s_addc_u32 s79, s40, s69
	s_and_b64 s[68:69], s[62:63], exec
	s_cselect_b32 s65, s79, s87
	s_cselect_b32 s73, s78, s86
	s_cmp_lg_u32 s4, 0
	s_cselect_b64 s[82:83], -1, 0
	s_add_u32 s69, s86, 0x100
	s_addc_u32 s71, s87, 0
	s_cmp_eq_u32 s4, 0
	s_cbranch_scc1 .LBB0_878
	s_add_u32 s4, s84, 0x100
	s_addc_u32 s5, s85, 0
	s_add_u32 s86, s86, 0x80080
	v_mov_b32_e32 v0, 0
	s_addc_u32 s87, s87, 0
	s_mov_b32 s68, -2
	v_mov_b32_e32 v1, v0
	v_mov_b32_e32 v2, v0
	v_mov_b32_e32 v3, v0
	v_mov_b32_e32 v4, v0
	v_mov_b32_e32 v5, v0
	v_mov_b32_e32 v6, v0
	v_mov_b32_e32 v7, v0
	v_mov_b32_e32 v8, v0
	v_mov_b32_e32 v9, v0
	v_mov_b32_e32 v10, v0
	v_mov_b32_e32 v11, v0
	v_mov_b32_e32 v12, v0
	v_mov_b32_e32 v13, v0
	v_mov_b32_e32 v14, v0
	v_mov_b32_e32 v15, v0
	v_mov_b32_e32 v16, v0
	v_mov_b32_e32 v17, v0
	v_mov_b32_e32 v18, v0
	v_mov_b32_e32 v19, v0
	v_mov_b32_e32 v20, v0
	v_mov_b32_e32 v21, v0
	v_mov_b32_e32 v22, v0
	v_mov_b32_e32 v23, v0
	v_mov_b32_e32 v24, v0
	v_mov_b32_e32 v25, v0
	v_mov_b32_e32 v26, v0
	v_mov_b32_e32 v27, v0
	v_mov_b32_e32 v28, v0
	v_mov_b32_e32 v29, v0
	v_mov_b32_e32 v30, v0
	v_mov_b32_e32 v31, v0
	v_mov_b32_e32 v32, v0
	v_mov_b32_e32 v33, v0
	v_mov_b32_e32 v34, v0
	v_mov_b32_e32 v35, v0

	v_mov_b64_e32 v[36:37], 0
	v_mov_b64_e32 v[38:39], 0
	v_mov_b64_e32 v[40:41], 0
	v_mov_b64_e32 v[42:43], 0
	v_mov_b64_e32 v[44:45], 0
	v_mov_b64_e32 v[46:47], 0
	v_mov_b64_e32 v[48:49], 0
	v_mov_b64_e32 v[50:51], 0
	v_mov_b64_e32 v[52:53], 0
	v_mov_b64_e32 v[54:55], 0
	v_mov_b64_e32 v[56:57], 0
	v_mov_b64_e32 v[58:59], 0
	v_mov_b64_e32 v[60:61], 0
	v_mov_b64_e32 v[62:63], 0
	v_mov_b64_e32 v[64:65], 0
	v_mov_b64_e32 v[66:67], 0
	v_mov_b64_e32 v[68:69], 0
	v_mov_b64_e32 v[70:71], 0
	v_mov_b64_e32 v[72:73], 0
	v_mov_b64_e32 v[74:75], 0
	v_mov_b64_e32 v[76:77], 0
	v_mov_b64_e32 v[78:79], 0
	v_mov_b64_e32 v[80:81], 0
	v_mov_b64_e32 v[82:83], 0
	v_mov_b64_e32 v[84:85], 0
	v_mov_b64_e32 v[86:87], 0
	v_mov_b64_e32 v[88:89], 0
	v_mov_b64_e32 v[90:91], 0
	v_mov_b64_e32 v[92:93], 0
	v_mov_b64_e32 v[94:95], 0
	s_nop 0
	s_nop 0
	s_nop 0
	s_nop 0
	s_nop 0
	s_nop 0
	s_nop 0
	s_nop 0
	s_nop 0
	s_nop 0
	s_nop 0
	s_nop 0
	s_nop 0

.LBB0_879:
	v_mov_b32_e32 v127, 0
	s_and_b64 vcc, exec, s[86:87]
	v_mov_b32_e32 v126, v127
	v_mov_b32_e32 v125, v127
	v_mov_b32_e32 v124, v127
	v_mov_b32_e32 v123, v127
	v_mov_b32_e32 v122, v127
	v_mov_b32_e32 v121, v127
	v_mov_b32_e32 v120, v127
	v_mov_b32_e32 v119, v127
	v_mov_b32_e32 v118, v127
	v_mov_b32_e32 v117, v127
	v_mov_b32_e32 v116, v127
	v_mov_b32_e32 v115, v127
	v_mov_b32_e32 v114, v127
	v_mov_b32_e32 v113, v127
	v_mov_b32_e32 v112, v127
	v_mov_b32_e32 v111, v127
	v_mov_b32_e32 v110, v127
	v_mov_b32_e32 v109, v127
	v_mov_b32_e32 v108, v127
	v_mov_b32_e32 v107, v127
	v_mov_b32_e32 v106, v127
	v_mov_b32_e32 v105, v127
	v_mov_b32_e32 v104, v127
	v_mov_b32_e32 v103, v127
	v_mov_b32_e32 v102, v127
	v_mov_b32_e32 v101, v127
	v_mov_b32_e32 v100, v127
	v_mov_b32_e32 v99, v127
	v_mov_b32_e32 v98, v127
	v_mov_b32_e32 v97, v127
	v_mov_b32_e32 v96, v127
	s_cbranch_vccz .LBB0_882
	s_cmp_lg_u32 s96, 0
	s_cselect_b64 s[86:87], -1, 0
	s_add_u32 s68, s73, 0x80000
	s_addc_u32 s4, s65, 0
	s_add_u32 s84, s84, 0x40080
	v_mov_b32_e32 v96, 0
	s_addc_u32 s85, s85, 0
	s_mov_b32 s5, -2
	v_mov_b64_e32 v[0:1], 0
	v_mov_b64_e32 v[2:3], 0
	v_mov_b64_e32 v[4:5], 0
	v_mov_b64_e32 v[6:7], 0
	v_mov_b64_e32 v[8:9], 0
	v_mov_b64_e32 v[10:11], 0
	v_mov_b64_e32 v[12:13], 0
	v_mov_b64_e32 v[14:15], 0
	v_mov_b64_e32 v[16:17], 0
	v_mov_b64_e32 v[18:19], 0
	v_mov_b64_e32 v[20:21], 0
	v_mov_b64_e32 v[22:23], 0
	v_mov_b64_e32 v[24:25], 0
	v_mov_b64_e32 v[26:27], 0
	v_mov_b64_e32 v[28:29], 0
	v_mov_b64_e32 v[30:31], 0
	v_mov_b64_e32 v[32:33], 0
	v_mov_b64_e32 v[34:35], 0
	v_mov_b32_e32 v97, 0
	v_mov_b64_e32 v[98:99], 0
	v_mov_b64_e32 v[100:101], 0
	v_mov_b64_e32 v[102:103], 0
	v_mov_b64_e32 v[104:105], 0
	v_mov_b64_e32 v[106:107], 0
	v_mov_b64_e32 v[108:109], 0
	v_mov_b64_e32 v[110:111], 0
	v_mov_b64_e32 v[112:113], 0
	v_mov_b64_e32 v[114:115], 0
	v_mov_b64_e32 v[116:117], 0
	v_mov_b64_e32 v[118:119], 0
	v_mov_b64_e32 v[120:121], 0
	v_mov_b64_e32 v[122:123], 0
	v_mov_b64_e32 v[124:125], 0
	v_mov_b64_e32 v[126:127], 0

	v_mov_b64_e32 v[36:37], 0
	v_mov_b64_e32 v[38:39], 0
	v_mov_b64_e32 v[40:41], 0
	v_mov_b64_e32 v[42:43], 0
	v_mov_b64_e32 v[44:45], 0
	v_mov_b64_e32 v[46:47], 0
	v_mov_b64_e32 v[48:49], 0
	v_mov_b64_e32 v[50:51], 0
	v_mov_b64_e32 v[52:53], 0
	v_mov_b64_e32 v[54:55], 0
	v_mov_b64_e32 v[56:57], 0
	v_mov_b64_e32 v[58:59], 0
	v_mov_b64_e32 v[60:61], 0
	v_mov_b64_e32 v[62:63], 0
	v_mov_b64_e32 v[64:65], 0
	v_mov_b64_e32 v[66:67], 0
	v_mov_b64_e32 v[68:69], 0
	v_mov_b64_e32 v[70:71], 0
	v_mov_b64_e32 v[72:73], 0
	v_mov_b64_e32 v[74:75], 0
	v_mov_b64_e32 v[76:77], 0
	v_mov_b64_e32 v[78:79], 0
	v_mov_b64_e32 v[80:81], 0
	v_mov_b64_e32 v[82:83], 0
	v_mov_b64_e32 v[84:85], 0
	v_mov_b64_e32 v[86:87], 0
	v_mov_b64_e32 v[88:89], 0
	v_mov_b64_e32 v[90:91], 0
	v_mov_b64_e32 v[92:93], 0
	v_mov_b64_e32 v[94:95], 0
	s_nop 0

.LBB0_970:
	s_ashr_i32 s65, s64, 31
	s_lshl_b64 s[78:79], s[64:65], 11
	s_add_u32 s78, s34, s78
	s_addc_u32 s79, s35, s79
	s_and_b64 s[80:81], s[2:3], exec
	s_cselect_b32 s65, s79, s5
	s_cselect_b32 s73, s78, s4
	s_ashr_i32 s67, s66, 31
	s_lshl_b64 s[80:81], s[66:67], 11
	s_add_u32 s80, s40, s80
	s_addc_u32 s81, s41, s81
	s_and_b64 s[82:83], s[2:3], exec
	s_cselect_b32 s67, s81, s7
	s_cselect_b32 s76, s80, s6
	s_add_u32 s4, s4, 0x40080
	s_addc_u32 s5, s5, 0
	s_add_u32 s86, s6, 0x100
	v_mov_b32_e32 v0, 0
	s_addc_u32 s87, s7, 0
	s_mov_b32 s88, -2
	v_mov_b32_e32 v1, 0
	v_mov_b64_e32 v[2:3], 0
	v_mov_b64_e32 v[4:5], 0
	v_mov_b64_e32 v[6:7], 0
	v_mov_b64_e32 v[8:9], 0
	v_mov_b64_e32 v[10:11], 0
	v_mov_b64_e32 v[12:13], 0
	v_mov_b64_e32 v[14:15], 0
	v_mov_b64_e32 v[16:17], 0
	v_mov_b64_e32 v[18:19], 0
	v_mov_b64_e32 v[20:21], 0
	v_mov_b64_e32 v[22:23], 0
	v_mov_b64_e32 v[24:25], 0
	v_mov_b64_e32 v[26:27], 0
	v_mov_b64_e32 v[28:29], 0
	v_mov_b64_e32 v[30:31], 0
	v_mov_b64_e32 v[32:33], 0
	v_mov_b64_e32 v[34:35], 0
	v_mov_b64_e32 v[36:37], 0
	v_mov_b64_e32 v[38:39], 0
	v_mov_b64_e32 v[40:41], 0
	v_mov_b64_e32 v[42:43], 0
	v_mov_b64_e32 v[44:45], 0
	v_mov_b64_e32 v[46:47], 0
	v_mov_b64_e32 v[48:49], 0
	v_mov_b64_e32 v[50:51], 0
	v_mov_b64_e32 v[52:53], 0
	v_mov_b64_e32 v[54:55], 0
	v_mov_b64_e32 v[56:57], 0
	v_mov_b64_e32 v[58:59], 0
	v_mov_b64_e32 v[60:61], 0
	v_mov_b64_e32 v[62:63], 0
	v_mov_b64_e32 v[64:65], 0
	v_mov_b64_e32 v[66:67], 0
	v_mov_b64_e32 v[68:69], 0
	v_mov_b64_e32 v[70:71], 0
	v_mov_b64_e32 v[72:73], 0
	v_mov_b64_e32 v[74:75], 0
	v_mov_b64_e32 v[76:77], 0
	v_mov_b64_e32 v[78:79], 0
	v_mov_b64_e32 v[80:81], 0
	v_mov_b64_e32 v[82:83], 0
	v_mov_b64_e32 v[84:85], 0
	v_mov_b64_e32 v[86:87], 0
	v_mov_b64_e32 v[88:89], 0
	v_mov_b64_e32 v[90:91], 0
	v_mov_b64_e32 v[92:93], 0
	v_mov_b64_e32 v[94:95], 0
	v_mov_b64_e32 v[96:97], 0
	v_mov_b64_e32 v[98:99], 0
	v_mov_b64_e32 v[100:101], 0
	v_mov_b64_e32 v[102:103], 0
	v_mov_b64_e32 v[104:105], 0
	v_mov_b64_e32 v[106:107], 0
	v_mov_b64_e32 v[108:109], 0
	v_mov_b64_e32 v[110:111], 0
	v_mov_b64_e32 v[112:113], 0
	v_mov_b64_e32 v[114:115], 0
	v_mov_b64_e32 v[116:117], 0
	v_mov_b64_e32 v[118:119], 0
	v_mov_b64_e32 v[124:125], 0
	v_mov_b64_e32 v[126:127], 0
	v_mov_b64_e32 v[132:133], 0
	v_mov_b64_e32 v[134:135], 0
	s_nop 0
	s_nop 0
	s_nop 0
	s_nop 0
	s_nop 0
	s_nop 0
	s_nop 0
	s_nop 0
	s_nop 0
	s_nop 0
	s_nop 0
	s_nop 0

.LBB0_1079:
	s_add_u32 s73, s38, 0x100
	v_mov_b32_e32 v0, 0
	s_addc_u32 s76, s39, 0
	s_mov_b32 s77, -2
	s_waitcnt lgkmcnt(0)
	v_mov_b32_e32 v1, 0
	v_mov_b64_e32 v[2:3], 0
	v_mov_b64_e32 v[4:5], 0
	v_mov_b64_e32 v[6:7], 0
	v_mov_b64_e32 v[8:9], 0
	v_mov_b64_e32 v[10:11], 0
	v_mov_b64_e32 v[12:13], 0
	v_mov_b64_e32 v[14:15], 0
	v_mov_b64_e32 v[16:17], 0
	v_mov_b64_e32 v[18:19], 0
	v_mov_b64_e32 v[20:21], 0
	v_mov_b64_e32 v[22:23], 0
	v_mov_b64_e32 v[24:25], 0
	v_mov_b64_e32 v[26:27], 0
	v_mov_b64_e32 v[28:29], 0
	v_mov_b64_e32 v[30:31], 0
	v_mov_b64_e32 v[32:33], 0
	v_mov_b64_e32 v[34:35], 0
	v_mov_b64_e32 v[36:37], 0
	v_mov_b64_e32 v[38:39], 0
	v_mov_b64_e32 v[40:41], 0
	v_mov_b64_e32 v[42:43], 0
	v_mov_b64_e32 v[44:45], 0
	v_mov_b64_e32 v[46:47], 0
	v_mov_b64_e32 v[48:49], 0
	v_mov_b64_e32 v[50:51], 0
	v_mov_b64_e32 v[52:53], 0
	v_mov_b64_e32 v[54:55], 0
	v_mov_b64_e32 v[56:57], 0
	v_mov_b64_e32 v[58:59], 0
	v_mov_b64_e32 v[60:61], 0
	v_mov_b64_e32 v[62:63], 0
	v_mov_b64_e32 v[64:65], 0
	v_mov_b64_e32 v[66:67], 0
	v_mov_b64_e32 v[68:69], 0
	v_mov_b64_e32 v[70:71], 0
	v_mov_b64_e32 v[72:73], 0
	v_mov_b64_e32 v[74:75], 0
	v_mov_b64_e32 v[76:77], 0
	v_mov_b64_e32 v[78:79], 0
	v_mov_b64_e32 v[80:81], 0
	v_mov_b64_e32 v[82:83], 0
	v_mov_b64_e32 v[84:85], 0
	v_mov_b64_e32 v[86:87], 0
	v_mov_b64_e32 v[88:89], 0
	v_mov_b64_e32 v[90:91], 0
	v_mov_b64_e32 v[92:93], 0
	v_mov_b64_e32 v[94:95], 0
	v_mov_b64_e32 v[96:97], 0
	v_mov_b64_e32 v[98:99], 0
	v_mov_b64_e32 v[100:101], 0
	v_mov_b64_e32 v[102:103], 0
	v_mov_b64_e32 v[104:105], 0
	v_mov_b64_e32 v[106:107], 0
	v_mov_b64_e32 v[108:109], 0
	v_mov_b64_e32 v[110:111], 0
	v_mov_b64_e32 v[112:113], 0
	v_mov_b64_e32 v[114:115], 0
	v_mov_b64_e32 v[116:117], 0
	v_mov_b64_e32 v[118:119], 0
	v_mov_b64_e32 v[120:121], 0
	v_mov_b64_e32 v[122:123], 0
	v_mov_b64_e32 v[124:125], 0
	v_mov_b64_e32 v[126:127], 0
	s_nop 0
	s_nop 0
	s_nop 0
	s_nop 0
	s_nop 0
	s_nop 0
	s_nop 0
	s_nop 0
	s_nop 0
	s_nop 0
	s_nop 0
	s_nop 0

.LBB0_1180:
	s_ashr_i32 s37, s36, 31
	s_lshl_b64 s[44:45], s[36:37], 11
	s_add_u32 s44, s34, s44
	s_addc_u32 s45, s35, s45
	s_and_b64 s[52:53], s[0:1], exec
	s_cselect_b32 s37, s45, s3
	s_cselect_b32 s52, s44, s2
	s_ashr_i32 s39, s38, 31
	s_lshl_b64 s[54:55], s[38:39], 11
	s_add_u32 s60, s67, s54
	s_addc_u32 s61, s78, s55
	s_and_b64 s[54:55], s[0:1], exec
	s_cselect_b32 s39, s61, s63
	s_cselect_b32 s53, s60, s62
	s_add_u32 s2, s2, 0x40080
	s_addc_u32 s3, s3, 0
	s_add_u32 s54, s62, 0x100
	v_mov_b32_e32 v0, 0
	s_addc_u32 s55, s63, 0
	s_mov_b32 s56, -2
	v_mov_b32_e32 v1, 0
	v_mov_b64_e32 v[2:3], 0
	v_mov_b64_e32 v[4:5], 0
	v_mov_b64_e32 v[6:7], 0
	v_mov_b64_e32 v[8:9], 0
	v_mov_b64_e32 v[10:11], 0
	v_mov_b64_e32 v[12:13], 0
	v_mov_b64_e32 v[14:15], 0
	v_mov_b64_e32 v[16:17], 0
	v_mov_b64_e32 v[18:19], 0
	v_mov_b64_e32 v[20:21], 0
	v_mov_b64_e32 v[22:23], 0
	v_mov_b64_e32 v[24:25], 0
	v_mov_b64_e32 v[26:27], 0
	v_mov_b64_e32 v[28:29], 0
	v_mov_b64_e32 v[30:31], 0
	v_mov_b64_e32 v[32:33], 0
	v_mov_b64_e32 v[34:35], 0
	v_mov_b64_e32 v[36:37], 0
	v_mov_b64_e32 v[38:39], 0
	v_mov_b64_e32 v[40:41], 0
	v_mov_b64_e32 v[42:43], 0
	v_mov_b64_e32 v[44:45], 0
	v_mov_b64_e32 v[46:47], 0
	v_mov_b64_e32 v[48:49], 0
	v_mov_b64_e32 v[50:51], 0
	v_mov_b64_e32 v[52:53], 0
	v_mov_b64_e32 v[54:55], 0
	v_mov_b64_e32 v[56:57], 0
	v_mov_b64_e32 v[58:59], 0
	v_mov_b64_e32 v[60:61], 0
	v_mov_b64_e32 v[62:63], 0
	v_mov_b64_e32 v[64:65], 0
	v_mov_b64_e32 v[66:67], 0
	v_mov_b64_e32 v[68:69], 0
	v_mov_b64_e32 v[70:71], 0
	v_mov_b64_e32 v[72:73], 0
	v_mov_b64_e32 v[74:75], 0
	v_mov_b64_e32 v[76:77], 0
	v_mov_b64_e32 v[78:79], 0
	v_mov_b64_e32 v[80:81], 0
	v_mov_b64_e32 v[82:83], 0
	v_mov_b64_e32 v[84:85], 0
	v_mov_b64_e32 v[86:87], 0
	v_mov_b64_e32 v[88:89], 0
	v_mov_b64_e32 v[90:91], 0
	v_mov_b64_e32 v[92:93], 0
	v_mov_b64_e32 v[94:95], 0
	v_mov_b64_e32 v[96:97], 0
	v_mov_b64_e32 v[98:99], 0
	v_mov_b64_e32 v[100:101], 0
	v_mov_b64_e32 v[102:103], 0
	v_mov_b64_e32 v[104:105], 0
	v_mov_b64_e32 v[106:107], 0
	v_mov_b64_e32 v[108:109], 0
	v_mov_b64_e32 v[110:111], 0
	v_mov_b64_e32 v[112:113], 0
	v_mov_b64_e32 v[114:115], 0
	v_mov_b64_e32 v[116:117], 0
	v_mov_b64_e32 v[118:119], 0
	v_mov_b64_e32 v[120:121], 0
	v_mov_b64_e32 v[122:123], 0
	v_mov_b64_e32 v[124:125], 0
	v_mov_b64_e32 v[126:127], 0
	s_nop 0
	s_nop 0
	s_nop 0
	s_nop 0
	s_nop 0
	s_nop 0
	s_nop 0
	s_nop 0
	s_nop 0
	s_nop 0
	s_nop 0
	s_nop 0

.LBB0_1529:
	s_ashr_i32 s11, s10, 31
	v_cmp_lt_i64_e32 vcc, s[14:15], v[164:165]
	s_lshl_b64 s[14:15], s[10:11], 11
	s_add_u32 s14, s41, s14
	s_addc_u32 s15, s42, s15
	s_and_b64 s[18:19], vcc, exec
	s_cselect_b32 s11, s15, s25
	s_cselect_b32 s61, s14, s24
	s_ashr_i32 s13, s12, 31
	s_lshl_b64 s[18:19], s[12:13], 11
	s_add_u32 s18, s43, s18
	s_addc_u32 s19, s44, s19
	s_and_b64 s[38:39], vcc, exec
	s_cselect_b32 s13, s19, s37
	s_cselect_b32 s62, s18, s36
	s_add_u32 s24, s24, 0x40080
	s_addc_u32 s25, s25, 0
	s_add_u32 s63, s36, 0x100
	v_mov_b32_e32 v0, 0
	s_addc_u32 s64, s37, 0
	s_mov_b32 s65, -2
	s_waitcnt lgkmcnt(0)
	v_mov_b32_e32 v1, v0
	v_mov_b32_e32 v2, v0
	v_mov_b32_e32 v3, v0
	v_mov_b32_e32 v4, v0
	v_mov_b32_e32 v5, v0
	v_mov_b32_e32 v6, v0
	v_mov_b32_e32 v7, v0
	v_mov_b32_e32 v16, v0
	v_mov_b32_e32 v17, v0
	v_mov_b32_e32 v18, v0
	v_mov_b32_e32 v19, v0
	v_mov_b32_e32 v20, v0
	v_mov_b32_e32 v21, v0
	v_mov_b32_e32 v22, v0
	v_mov_b32_e32 v23, v0
	v_mov_b32_e32 v32, v0
	v_mov_b32_e32 v33, v0
	v_mov_b32_e32 v34, v0
	v_mov_b32_e32 v35, v0

	v_mov_b64_e32 v[8:9], 0
	v_mov_b64_e32 v[10:11], 0
	v_mov_b64_e32 v[12:13], 0
	v_mov_b64_e32 v[14:15], 0
	v_mov_b64_e32 v[24:25], 0
	v_mov_b64_e32 v[26:27], 0
	v_mov_b64_e32 v[28:29], 0
	v_mov_b64_e32 v[30:31], 0
	v_mov_b64_e32 v[36:37], 0
	v_mov_b64_e32 v[38:39], 0
	v_mov_b64_e32 v[40:41], 0
	v_mov_b64_e32 v[42:43], 0
	v_mov_b64_e32 v[44:45], 0
	v_mov_b64_e32 v[46:47], 0
	v_mov_b64_e32 v[48:49], 0
	v_mov_b64_e32 v[50:51], 0
	v_mov_b64_e32 v[52:53], 0
	v_mov_b64_e32 v[54:55], 0
	v_mov_b64_e32 v[56:57], 0
	v_mov_b64_e32 v[58:59], 0
	v_mov_b64_e32 v[60:61], 0
	v_mov_b64_e32 v[62:63], 0
	v_mov_b64_e32 v[64:65], 0
	v_mov_b64_e32 v[66:67], 0
	v_mov_b64_e32 v[68:69], 0
	v_mov_b64_e32 v[70:71], 0
	v_mov_b64_e32 v[72:73], 0
	v_mov_b64_e32 v[74:75], 0
	v_mov_b64_e32 v[76:77], 0
	v_mov_b64_e32 v[78:79], 0
	v_mov_b64_e32 v[80:81], 0
	v_mov_b64_e32 v[82:83], 0
	v_mov_b64_e32 v[84:85], 0
	v_mov_b64_e32 v[86:87], 0
	v_mov_b64_e32 v[88:89], 0
	v_mov_b64_e32 v[90:91], 0
	v_mov_b64_e32 v[92:93], 0
	v_mov_b64_e32 v[94:95], 0
	v_mov_b64_e32 v[96:97], 0
	v_mov_b64_e32 v[98:99], 0
	v_mov_b64_e32 v[100:101], 0
	v_mov_b64_e32 v[102:103], 0
	v_mov_b64_e32 v[104:105], 0
	v_mov_b64_e32 v[106:107], 0
	v_mov_b64_e32 v[108:109], 0
	v_mov_b64_e32 v[110:111], 0
	v_mov_b64_e32 v[112:113], 0
	v_mov_b64_e32 v[114:115], 0
	v_mov_b64_e32 v[116:117], 0
	v_mov_b64_e32 v[118:119], 0
	v_mov_b64_e32 v[120:121], 0
	v_mov_b64_e32 v[122:123], 0
	v_mov_b64_e32 v[124:125], 0
	v_mov_b64_e32 v[126:127], 0
	s_nop 0
	s_nop 0
	s_nop 0
	s_nop 0
	s_nop 0
	s_nop 0
	s_nop 0
	s_nop 0
	s_nop 0
	s_nop 0
	s_nop 0
	s_nop 0
	s_nop 0

.LBB0_1656:
	s_ashr_i32 s39, s38, 31
	s_lshl_b64 s[6:7], s[38:39], 11
	s_add_u32 s44, s34, s6
	s_addc_u32 s45, s35, s7
	s_and_b64 s[6:7], s[40:41], exec
	s_cselect_b32 s3, s45, s49
	s_cselect_b32 s5, s44, s48
	s_ashr_i32 s43, s42, 31
	s_lshl_b64 s[6:7], s[42:43], 11
	s_add_u32 s46, s37, s6
	s_addc_u32 s47, s52, s7
	s_and_b64 s[6:7], s[40:41], exec
	s_cselect_b32 s39, s47, s51
	s_cselect_b32 s43, s46, s50
	s_cmp_lg_u32 s54, 0
	s_cselect_b64 s[6:7], -1, 0
	s_add_u32 s85, s50, 0x100
	s_addc_u32 s86, s51, 0
	s_cmp_eq_u32 s54, 0
	s_cbranch_scc1 .LBB0_1660
	s_add_u32 s56, s48, 0x100
	s_addc_u32 s57, s49, 0
	s_add_u32 s50, s50, 0x80080
	v_mov_b32_e32 v0, 0
	s_addc_u32 s51, s51, 0
	s_mov_b32 s58, -2
	v_mov_b32_e32 v1, 0
	v_mov_b64_e32 v[2:3], 0
	v_mov_b64_e32 v[4:5], 0
	v_mov_b64_e32 v[6:7], 0
	v_mov_b64_e32 v[8:9], 0
	v_mov_b64_e32 v[10:11], 0
	v_mov_b64_e32 v[12:13], 0
	v_mov_b64_e32 v[14:15], 0
	v_mov_b64_e32 v[16:17], 0
	v_mov_b64_e32 v[18:19], 0
	v_mov_b64_e32 v[20:21], 0
	v_mov_b64_e32 v[22:23], 0
	v_mov_b64_e32 v[24:25], 0
	v_mov_b64_e32 v[26:27], 0
	v_mov_b64_e32 v[28:29], 0
	v_mov_b64_e32 v[30:31], 0
	v_mov_b64_e32 v[32:33], 0
	v_mov_b64_e32 v[34:35], 0
	v_mov_b64_e32 v[36:37], 0
	v_mov_b64_e32 v[38:39], 0
	v_mov_b64_e32 v[40:41], 0
	v_mov_b64_e32 v[42:43], 0
	v_mov_b64_e32 v[44:45], 0
	v_mov_b64_e32 v[46:47], 0
	v_mov_b64_e32 v[48:49], 0
	v_mov_b64_e32 v[50:51], 0
	v_mov_b64_e32 v[52:53], 0
	v_mov_b64_e32 v[54:55], 0
	v_mov_b64_e32 v[56:57], 0
	v_mov_b64_e32 v[58:59], 0
	v_mov_b64_e32 v[60:61], 0
	v_mov_b64_e32 v[62:63], 0
	v_mov_b64_e32 v[64:65], 0
	v_mov_b64_e32 v[66:67], 0
	v_mov_b64_e32 v[68:69], 0
	v_mov_b64_e32 v[70:71], 0
	v_mov_b64_e32 v[72:73], 0
	v_mov_b64_e32 v[74:75], 0
	v_mov_b64_e32 v[76:77], 0
	v_mov_b64_e32 v[78:79], 0
	v_mov_b64_e32 v[80:81], 0
	v_mov_b64_e32 v[82:83], 0
	v_mov_b64_e32 v[84:85], 0
	v_mov_b64_e32 v[86:87], 0
	v_mov_b64_e32 v[88:89], 0
	v_mov_b64_e32 v[90:91], 0
	v_mov_b64_e32 v[92:93], 0
	v_mov_b64_e32 v[94:95], 0
	s_nop 0
	s_nop 0
	s_nop 0
	s_nop 0
	s_nop 0
	s_nop 0
	s_nop 0
	s_nop 0
	s_nop 0
	s_nop 0
	s_nop 0
	s_nop 0

.LBB0_1747:
	s_ashr_i32 s49, s48, 31
	s_lshl_b64 s[6:7], s[48:49], 11
	s_add_u32 s56, s34, s6
	s_addc_u32 s57, s35, s7
	s_and_b64 s[6:7], s[50:51], exec
	s_cselect_b32 s3, s57, s9
	s_cselect_b32 s5, s56, s8
	s_ashr_i32 s55, s54, 31
	s_lshl_b64 s[6:7], s[54:55], 11
	s_add_u32 s58, s45, s6
	s_addc_u32 s59, s47, s7
	s_and_b64 s[6:7], s[50:51], exec
	s_cselect_b32 s49, s59, s61
	s_cselect_b32 s52, s58, s60
	s_cmp_lg_u32 s62, 0
	s_cselect_b64 s[6:7], -1, 0
	s_add_u32 s53, s60, 0x100
	s_addc_u32 s55, s61, 0
	s_cmp_eq_u32 s62, 0
	s_cbranch_scc1 .LBB0_1800
	s_add_u32 s64, s8, 0x100
	s_addc_u32 s65, s9, 0
	s_add_u32 s60, s60, 0x80080
	v_mov_b32_e32 v14, 0
	s_addc_u32 s61, s61, 0
	s_mov_b32 s66, -2
	v_mov_b32_e32 v15, v14
	v_mov_b32_e32 v16, v14
	v_mov_b32_e32 v17, v14
	v_mov_b32_e32 v22, v14
	v_mov_b32_e32 v23, v14
	v_mov_b32_e32 v24, v14
	v_mov_b32_e32 v25, v14
	v_mov_b32_e32 v34, v14
	v_mov_b32_e32 v35, v14

	v_mov_b64_e32 v[36:37], 0
	v_mov_b64_e32 v[42:43], 0
	v_mov_b64_e32 v[44:45], 0
	v_mov_b64_e32 v[50:51], 0
	v_mov_b64_e32 v[52:53], 0
	v_mov_b64_e32 v[54:55], 0
	v_mov_b64_e32 v[56:57], 0
	v_mov_b64_e32 v[58:59], 0
	v_mov_b64_e32 v[60:61], 0
	v_mov_b64_e32 v[62:63], 0
	v_mov_b64_e32 v[64:65], 0
	v_mov_b64_e32 v[66:67], 0
	v_mov_b64_e32 v[68:69], 0
	v_mov_b64_e32 v[70:71], 0
	v_mov_b64_e32 v[72:73], 0
	v_mov_b64_e32 v[74:75], 0
	v_mov_b64_e32 v[76:77], 0
	v_mov_b64_e32 v[78:79], 0
	v_mov_b64_e32 v[80:81], 0
	v_mov_b64_e32 v[82:83], 0
	v_mov_b64_e32 v[84:85], 0
	v_mov_b64_e32 v[86:87], 0
	v_mov_b64_e32 v[88:89], 0
	v_mov_b64_e32 v[90:91], 0
	v_mov_b64_e32 v[92:93], 0
	v_mov_b64_e32 v[94:95], 0
	v_mov_b64_e32 v[96:97], 0
	v_mov_b64_e32 v[98:99], 0
	v_mov_b64_e32 v[100:101], 0
	v_mov_b64_e32 v[102:103], 0
	v_mov_b64_e32 v[104:105], 0
	v_mov_b64_e32 v[106:107], 0
	v_mov_b64_e32 v[108:109], 0
	v_mov_b64_e32 v[110:111], 0
	v_mov_b64_e32 v[112:113], 0
	v_mov_b64_e32 v[114:115], 0
	v_mov_b64_e32 v[116:117], 0
	v_mov_b64_e32 v[118:119], 0
	v_mov_b64_e32 v[120:121], 0
	v_mov_b64_e32 v[122:123], 0
	v_mov_b64_e32 v[124:125], 0
	v_mov_b64_e32 v[126:127], 0
	v_mov_b64_e32 v[128:129], 0
	s_nop 0
	s_nop 0
	s_nop 0
	s_nop 0
	s_nop 0
	s_nop 0
	s_nop 0
	s_nop 0
	s_nop 0
	s_nop 0
	s_nop 0
	s_nop 0
	s_nop 0

.LBB0_1751:
	s_cmp_lg_u32 s92, 0
	s_cselect_b64 s[60:61], -1, 0
	s_add_u32 s68, s52, 0x80000
	s_addc_u32 s69, s49, 0
	s_add_u32 s8, s8, 0x40080
	v_mov_b32_e32 v2, 0
	s_addc_u32 s9, s9, 0
	s_mov_b32 s72, -2
	v_mov_b32_e32 v3, v2
	v_mov_b32_e32 v4, v2
	v_mov_b32_e32 v5, v2
	v_mov_b32_e32 v6, v2
	v_mov_b32_e32 v7, v2
	v_mov_b32_e32 v8, v2
	v_mov_b32_e32 v9, v2
	v_mov_b32_e32 v10, v2
	v_mov_b32_e32 v11, v2
	v_mov_b32_e32 v12, v2
	v_mov_b32_e32 v13, v2
	v_mov_b32_e32 v18, v2
	v_mov_b32_e32 v19, v2
	v_mov_b32_e32 v20, v2
	v_mov_b32_e32 v21, v2
	v_mov_b32_e32 v26, v2
	v_mov_b32_e32 v27, v2
	v_mov_b32_e32 v28, v2
	v_mov_b32_e32 v29, v2
	v_mov_b32_e32 v30, v2
	v_mov_b32_e32 v31, v2
	v_mov_b32_e32 v32, v2
	v_mov_b32_e32 v33, v2

	v_mov_b64_e32 v[14:15], 0
	v_mov_b64_e32 v[16:17], 0
	v_mov_b64_e32 v[22:23], 0
	v_mov_b64_e32 v[24:25], 0
	v_mov_b64_e32 v[34:35], 0
	v_mov_b64_e32 v[36:37], 0
	v_mov_b64_e32 v[38:39], 0
	v_mov_b64_e32 v[40:41], 0
	v_mov_b64_e32 v[42:43], 0
	v_mov_b64_e32 v[44:45], 0
	v_mov_b64_e32 v[46:47], 0
	v_mov_b64_e32 v[48:49], 0
	v_mov_b64_e32 v[50:51], 0
	v_mov_b64_e32 v[52:53], 0
	v_mov_b64_e32 v[54:55], 0
	v_mov_b64_e32 v[56:57], 0
	v_mov_b64_e32 v[58:59], 0
	v_mov_b64_e32 v[60:61], 0
	v_mov_b64_e32 v[62:63], 0
	v_mov_b64_e32 v[64:65], 0
	v_mov_b64_e32 v[66:67], 0
	v_mov_b64_e32 v[68:69], 0
	v_mov_b64_e32 v[70:71], 0
	v_mov_b64_e32 v[72:73], 0
	v_mov_b64_e32 v[74:75], 0
	v_mov_b64_e32 v[76:77], 0
	v_mov_b64_e32 v[78:79], 0
	v_mov_b64_e32 v[80:81], 0
	v_mov_b64_e32 v[82:83], 0
	v_mov_b64_e32 v[84:85], 0
	v_mov_b64_e32 v[86:87], 0
	v_mov_b64_e32 v[88:89], 0
	v_mov_b64_e32 v[90:91], 0
	v_mov_b64_e32 v[92:93], 0
	v_mov_b64_e32 v[94:95], 0
	v_mov_b64_e32 v[96:97], 0
	v_mov_b64_e32 v[98:99], 0
	v_mov_b64_e32 v[100:101], 0
	v_mov_b64_e32 v[102:103], 0
	v_mov_b64_e32 v[104:105], 0
	v_mov_b64_e32 v[106:107], 0
	v_mov_b64_e32 v[108:109], 0
	v_mov_b64_e32 v[110:111], 0
	v_mov_b64_e32 v[112:113], 0
	v_mov_b64_e32 v[114:115], 0
	v_mov_b64_e32 v[116:117], 0
	v_mov_b64_e32 v[118:119], 0
	v_mov_b64_e32 v[120:121], 0
	v_mov_b64_e32 v[122:123], 0
	v_mov_b64_e32 v[124:125], 0
	v_mov_b64_e32 v[126:127], 0
	v_mov_b64_e32 v[128:129], 0
	s_nop 0

.LBB0_1881:
	s_add_u32 s56, s24, 0x100
	v_mov_b32_e32 v0, 0
	s_addc_u32 s57, s25, 0
	s_mov_b32 s58, -2
	v_mov_b32_e32 v1, v0
	v_mov_b32_e32 v2, v0
	v_mov_b32_e32 v3, v0
	v_mov_b32_e32 v4, v0
	v_mov_b32_e32 v5, v0
	v_mov_b32_e32 v6, v0
	v_mov_b32_e32 v7, v0
	v_mov_b32_e32 v16, v0
	v_mov_b32_e32 v17, v0
	v_mov_b32_e32 v18, v0
	v_mov_b32_e32 v19, v0
	v_mov_b32_e32 v20, v0
	v_mov_b32_e32 v21, v0
	v_mov_b32_e32 v22, v0
	v_mov_b32_e32 v23, v0
	v_mov_b32_e32 v32, v0
	v_mov_b32_e32 v33, v0
	v_mov_b32_e32 v34, v0
	v_mov_b32_e32 v35, v0

	v_mov_b64_e32 v[8:9], 0
	v_mov_b64_e32 v[10:11], 0
	v_mov_b64_e32 v[12:13], 0
	v_mov_b64_e32 v[14:15], 0
	v_mov_b64_e32 v[24:25], 0
	v_mov_b64_e32 v[26:27], 0
	v_mov_b64_e32 v[28:29], 0
	v_mov_b64_e32 v[30:31], 0
	v_mov_b64_e32 v[36:37], 0
	v_mov_b64_e32 v[38:39], 0
	v_mov_b64_e32 v[40:41], 0
	v_mov_b64_e32 v[42:43], 0
	v_mov_b64_e32 v[44:45], 0
	v_mov_b64_e32 v[46:47], 0
	v_mov_b64_e32 v[48:49], 0
	v_mov_b64_e32 v[50:51], 0
	v_mov_b64_e32 v[52:53], 0
	v_mov_b64_e32 v[54:55], 0
	v_mov_b64_e32 v[56:57], 0
	v_mov_b64_e32 v[58:59], 0
	v_mov_b64_e32 v[60:61], 0
	v_mov_b64_e32 v[62:63], 0
	v_mov_b64_e32 v[64:65], 0
	v_mov_b64_e32 v[66:67], 0
	v_mov_b64_e32 v[68:69], 0
	v_mov_b64_e32 v[70:71], 0
	v_mov_b64_e32 v[72:73], 0
	v_mov_b64_e32 v[74:75], 0
	v_mov_b64_e32 v[76:77], 0
	v_mov_b64_e32 v[78:79], 0
	v_mov_b64_e32 v[80:81], 0
	v_mov_b64_e32 v[82:83], 0
	v_mov_b64_e32 v[84:85], 0
	v_mov_b64_e32 v[86:87], 0
	v_mov_b64_e32 v[88:89], 0
	v_mov_b64_e32 v[90:91], 0
	v_mov_b64_e32 v[92:93], 0
	v_mov_b64_e32 v[94:95], 0
	v_mov_b64_e32 v[96:97], 0
	v_mov_b64_e32 v[98:99], 0
	v_mov_b64_e32 v[100:101], 0
	v_mov_b64_e32 v[102:103], 0
	v_mov_b64_e32 v[104:105], 0
	v_mov_b64_e32 v[106:107], 0
	v_mov_b64_e32 v[108:109], 0
	v_mov_b64_e32 v[110:111], 0
	v_mov_b64_e32 v[112:113], 0
	v_mov_b64_e32 v[114:115], 0
	v_mov_b64_e32 v[116:117], 0
	v_mov_b64_e32 v[118:119], 0
	v_mov_b64_e32 v[120:121], 0
	v_mov_b64_e32 v[122:123], 0
	v_mov_b64_e32 v[124:125], 0
	v_mov_b64_e32 v[126:127], 0
	s_nop 0
	s_nop 0
	s_nop 0
	s_nop 0
	s_nop 0
	s_nop 0
	s_nop 0
	s_nop 0
	s_nop 0
	s_nop 0
	s_nop 0
	s_nop 0
	s_nop 0
